# layer-boundary seam as panel barrier: layer-1 weights converted in l0 FFN2-in idle slots are published by their writers (L2 writeback + arrival counter) and the seam waits on that counter
# speedup vs baseline: 1.0244x; 1.0030x over previous
; __global__ void __launch_bounds__(512, 2) fwd_kernel(Args A_unused) {
;     ...
;                     if ((s == 0 || s == 5) && blockIdx.x >= 128) {
;                         const int wv_ = (int)(blockIdx.x - 128) * 8 + wvx;
;                         if (l == 0 && s == 0) weight_copies(A, lds, I_LAYER, I_LAYER + I_FIN, wv_, 128 * 8);
;                         if (l == 0 && s == 5) { weight_copies(A, lds, I_LAYER + R_F1OUT, I_LAYER + R_F2OUT, wv_, 128 * 8);
;                                                 weight_copies(A, lds, I_LAYER + R_WIN, I_LAYER + R_WOUT, wv_, 128 * 8); }
.Lmy_copy_done:
	s_waitcnt vmcnt(0) lgkmcnt(0)
	s_barrier
	s_mov_b64 s[4:5], exec
	v_readlane_b32 s6, v238, 8
	v_readlane_b32 s7, v238, 9
	s_nop 1
	s_and_b64 s[6:7], s[4:5], s[6:7]
	s_mov_b64 exec, s[6:7]
	s_cbranch_execz .Lmy_copy_skip
	buffer_wbl2 sc1
	s_waitcnt vmcnt(0)
	v_readlane_b32 s6, v238, 30
	v_readlane_b32 s7, v238, 31
	v_mov_b32_e32 v1, 1
	s_nop 4
	global_atomic_add v0, v1, s[6:7] offset:-480
.Lmy_copy_skip:
	s_mov_b64 exec, s[4:5]

; __device__ __forceinline__ void xcd_barrier(const XcdBarrier& b) {
;     asm volatile("s_waitcnt vmcnt(0)" ::: "memory");
;     __syncthreads();
;     if (threadIdx.x == 0) {
; __global__ void __launch_bounds__(512, 2) fwd_kernel(Args A_unused) {
;     ...
;         if (ph + 1 < ph_hi) {
;             if (ph_lo < 0) grid.sync();
;             xcd_barrier(xbar);
;         }
.LBB0_893:
	v_mov_b32_e32 v1, 0x20018
	ds_read_b32 v1, v1
	v_readlane_b32 s10, v238, 0
	v_readlane_b32 s13, v237, 62
	s_waitcnt vmcnt(0) lgkmcnt(0)
	s_nop 0
	v_readfirstlane_b32 s11, v1
	s_nop 3
	s_mul_i32 s11, s11, 0xcf9c
	s_bitcmp1_b32 s11, s10
	s_cbranch_scc0 .Lmy_global_bar
	s_lshl_b32 s12, 2, s10
	s_add_i32 s12, s12, -1
	s_and_b32 s12, s12, 0xcf9c
	s_bcnt1_i32_b32 s12, s12
	s_lshl_b32 s12, s12, 2
	s_and_b32 s6, s13, 7
	s_lshl_b32 s6, s6, 3
	s_bfe_u32 s7, s13, 0x30003
	s_add_i32 s13, s6, s7
	s_mul_i32 s6, s13, 10
	s_mul_i32 s6, s6, 0x1746
	s_lshr_b32 s6, s6, 16
	s_add_i32 s7, s6, 1
	s_min_u32 s7, s7, s13
	s_cmp_eq_u32 s10, 4
	s_cselect_b32 s11, 1, 0
	s_cmp_eq_u32 s10, 11
	s_cselect_b32 s11, 1, s11
	s_cmp_eq_u32 s11, 1
	s_cselect_b32 s6, s6, s13
	s_cselect_b32 s7, s7, s13
	s_lshl_b32 s13, s13, 6
	s_lshl_b32 s6, s6, 6
	s_lshl_b32 s7, s7, 6
	s_addk_i32 s13, 0x1000
	s_addk_i32 s6, 0x1000
	s_addk_i32 s7, 0x1000
	v_mov_b32_e32 v1, s13
	v_mov_b32_e32 v2, s6
	v_mov_b32_e32 v3, s7
	v_readlane_b32 s6, v238, 30
	v_readlane_b32 s7, v238, 31
	v_mov_b32_e32 v8, 1
	s_mov_b32 s13, 0
	s_sub_u32 s6, s6, 0x4200
	s_subb_u32 s7, s7, 0
	s_cmp_eq_u32 s10, 9
	s_cselect_b32 s11, 0x80, 0
	v_mov_b32_e32 v9, 0x4020
	s_nop 4
	global_atomic_add v1, v8, s[6:7]
.Lmy_panel_spin:
	global_load_dword v4, v1, s[6:7] sc1
	global_load_dword v5, v2, s[6:7] sc1
	global_load_dword v6, v3, s[6:7] sc1
	global_load_dword v7, v9, s[6:7] sc1
	s_add_i32 s13, s13, 1
	s_waitcnt vmcnt(0)
	v_min3_u32 v4, v4, v5, v6
	v_cmp_le_u32_e64 s[14:15], s12, v4
	v_cmp_le_u32_e64 s[16:17], s11, v7
	s_nop 1
	s_and_b64 vcc, s[14:15], s[16:17]
	s_cbranch_vccnz .Lmy_panel_done
	s_cmp_lt_u32 s13, 0x200000
	s_cbranch_scc0 .Lmy_panel_done
	s_sleep 1
	s_branch .Lmy_panel_spin
